# P5/P6 start stagger: odd XCD-local workgroups start 0.7 us late (de-phase the chip-wide K-tile lock-step)
# speedup vs baseline: 1.0031x; 1.0031x over previous
; #define LAS __attribute__((address_space(3)))
;     DI bool next(int i, Unit& u) const {
;         const long L = (long)i * G + c; if (L >= nwg) return false;
;         int wgid = (int)L; { const int q = nwg / NXCD, r = nwg % NXCD, xcd = wgid % NXCD, off = wgid / NXCD; wgid = (xcd < r ? xcd * (q + 1) : r * (q + 1) + (xcd - r) * q) + off; }
;         const int nig = WGM * nN, gid = wgid / nig, fm = gid * WGM, gsz = (nM - fm) < WGM ? (nM - fm) : WGM;
;         u.pm = fm + ((wgid % nig) % gsz); u.pn = (wgid % nig) / gsz; return true;
; __global__ void __launch_bounds__(512, 2) mega(Params p) {
;     ...
;     if (PH(5)) {
;         pg8::Gemm g; g.A0 = (const bf16_t*)(p.ws + WS_ZG); g.A1 = (const bf16_t*)(p.ws + WS_YB) - 2048; g.B0 = (const bf16_t*)(p.ws + WS_WAT); g.B1 = (const bf16_t*)(p.ws + WS_WBT) - 2048;
;         g.lda = DM; g.ldb = DM; g.M = S; g.N = DM; g.K = 2 * DM; g.ksplit = DM / 64;
;         pg8::StaticOrder so; so.init(g.M, g.N, (int)gridDim.x, (int)blockIdx.x);
;         EpiMergeMid e; e.ws = p.ws;
;         pg8::gemm_phase<EpiMergeMid>((LAS unsigned char*)shm, g, so, e);
.LBB0_431:
	s_or_b64 exec, exec, s[4:5]
	v_cmp_gt_i32_e32 vcc, 6, v0
	v_cmp_lt_i32_e64 s[4:5], 5, v1
	s_and_b64 s[4:5], vcc, s[4:5]
	s_and_saveexec_b64 s[6:7], s[4:5]
	s_cbranch_execz .LBB0_456
	s_bitcmp1_b32 s2, 3
	s_cbranch_scc0 .Lp5_nostag
	s_sleep 19
.Lp5_nostag:
	s_cmpk_gt_i32 s2, 0x1ff
	v_readfirstlane_b32 s52, v202
	s_cbranch_scc1 .LBB0_456
	s_ashr_i32 s53, s2, 31
	s_load_dwordx2 s[8:9], s[0:1], 0x80
	s_lshr_b32 s4, s53, 29
	s_add_i32 s11, s2, s4
	s_and_b32 s4, s11, -8
	s_sub_i32 s12, s2, s4
	s_cmp_gt_i32 s12, -1
	s_cbranch_scc0 .LBB0_435
	s_lshl_b32 s10, s12, 6
	s_cbranch_execz .LBB0_436
	s_branch .LBB0_437

; #define LAS __attribute__((address_space(3)))
;     DI bool next(int i, Unit& u) const {
;         const long L = (long)i * G + c; if (L >= nwg) return false;
;         int wgid = (int)L; { const int q = nwg / NXCD, r = nwg % NXCD, xcd = wgid % NXCD, off = wgid / NXCD; wgid = (xcd < r ? xcd * (q + 1) : r * (q + 1) + (xcd - r) * q) + off; }
;         const int nig = WGM * nN, gid = wgid / nig, fm = gid * WGM, gsz = (nM - fm) < WGM ? (nM - fm) : WGM;
;         u.pm = fm + ((wgid % nig) % gsz); u.pn = (wgid % nig) / gsz; return true;
; __global__ void __launch_bounds__(512, 2) mega(Params p) {
;     ...
;     if (PH(6)) {
;         pg8::Gemm g; g.A0 = (const bf16_t*)(p.ws + WS_MRG); g.A1 = g.A0; g.B0 = (const bf16_t*)(p.ws + WS_WOT); g.B1 = g.B0;
;         g.lda = DM; g.ldb = DM; g.M = S; g.N = DM; g.K = DM; g.ksplit = DM / 64;
;         pg8::StaticOrder so; so.init(g.M, g.N, (int)gridDim.x, (int)blockIdx.x);
;         EpiOut e; e.ws = p.ws;
;         pg8::gemm_phase<EpiOut>((LAS unsigned char*)shm, g, so, e);
.LBB0_506:
	s_or_b64 exec, exec, s[4:5]
	v_cmp_gt_i32_e32 vcc, 7, v0
	v_cmp_lt_i32_e64 s[4:5], 6, v1
	s_and_b64 s[4:5], vcc, s[4:5]
	s_and_saveexec_b64 s[8:9], s[4:5]
	s_cbranch_execz .LBB0_545
	s_bitcmp1_b32 s2, 3
	s_cbranch_scc0 .Lp6_nostag
	s_sleep 19
.Lp6_nostag:
	s_load_dwordx2 s[10:11], s[0:1], 0x80
	s_cmpk_lt_i32 s2, 0x200
	s_cselect_b64 s[4:5], -1, 0
	s_cmpk_gt_i32 s2, 0x1ff
	v_readfirstlane_b32 s50, v202
	s_cbranch_scc1 .LBB0_513
	s_ashr_i32 s6, s2, 31
	s_lshr_b32 s6, s6, 29
	s_add_i32 s14, s2, s6
	s_and_b32 s6, s14, -8
	s_sub_i32 s12, s2, s6
	s_cmp_gt_i32 s12, -1
	s_cbranch_scc0 .LBB0_510
	s_lshl_b32 s13, s12, 6
	s_ashr_i32 s6, s14, 3
	s_cbranch_execz .LBB0_511
	s_branch .LBB0_512
